# DeltaNet prep step B (conv+SiLU+L2norm) hand-written: scalar row addressing, rcp-based SiLU, DPP row reductions, hw bf16 packs; GLA prep q_dec section compact
# speedup vs baseline: 1.5839x; 1.0222x over previous
.LBB0_213:
	v_readfirstlane_b32 s50, v34
	v_readlane_b32 s46, v252, 37
	v_readlane_b32 s47, v252, 38
	s_mul_hi_i32 s4, s80, 0xfe03f81
	s_lshr_b32 s5, s4, 31
	s_ashr_i32 s4, s4, 3
	s_add_i32 s4, s4, s5
	s_mul_i32 s5, s4, 0x81
	s_sub_i32 s5, s80, s5
	s_and_b32 s4, s4, 3
	s_lshl_b32 s4, s4, 8
	s_add_i32 s4, s4, 0xa00
	s_add_u32 s48, s46, s4
	s_addc_u32 s49, s47, 0
	s_lshl_b32 s5, s5, 6
	s_lshr_b32 s50, s50, 1
	s_add_i32 s5, s5, s50
	s_add_i32 s51, s5, -51
	s_lshl_b32 s52, s50, 2
	v_and_b32_e32 v69, 63, v35
	v_lshlrev_b32_e32 v69, 2, v69
	s_mov_b32 s53, 0
	s_mov_b32 s54, 0x3fb8aa3b
	s_mov_b64 s[0:1], 0x400
	s_waitcnt vmcnt(0)
.Ldnb_group:
	s_add_i32 s4, s51, 0
	s_max_i32 s4, s4, 0
	s_add_i32 s4, s4, s95
	s_mul_i32 s4, s4, 0x1a00
	s_add_u32 s6, s48, s4
	s_addc_u32 s7, s49, 0
	global_load_dword v188, v69, s[6:7]
	global_load_dword v189, v69, s[6:7] offset:1024
	global_load_dword v190, v69, s[6:7] offset:2048
	s_add_i32 s4, s51, 1
	s_max_i32 s4, s4, 0
	s_add_i32 s4, s4, s95
	s_mul_i32 s4, s4, 0x1a00
	s_add_u32 s6, s48, s4
	s_addc_u32 s7, s49, 0
	global_load_dword v191, v69, s[6:7]
	global_load_dword v192, v69, s[6:7] offset:1024
	global_load_dword v193, v69, s[6:7] offset:2048
	s_add_i32 s4, s51, 2
	s_max_i32 s4, s4, 0
	s_add_i32 s4, s4, s95
	s_mul_i32 s4, s4, 0x1a00
	s_add_u32 s6, s48, s4
	s_addc_u32 s7, s49, 0
	global_load_dword v194, v69, s[6:7]
	global_load_dword v195, v69, s[6:7] offset:1024
	global_load_dword v196, v69, s[6:7] offset:2048
	s_add_i32 s4, s51, 3
	s_max_i32 s4, s4, 0
	s_add_i32 s4, s4, s95
	s_mul_i32 s4, s4, 0x1a00
	s_add_u32 s6, s48, s4
	s_addc_u32 s7, s49, 0
	global_load_dword v197, v69, s[6:7]
	global_load_dword v198, v69, s[6:7] offset:1024
	global_load_dword v199, v69, s[6:7] offset:2048
	s_add_i32 s4, s51, 4
	s_max_i32 s4, s4, 0
	s_add_i32 s4, s4, s95
	s_mul_i32 s4, s4, 0x1a00
	s_add_u32 s6, s48, s4
	s_addc_u32 s7, s49, 0
	global_load_dword v200, v69, s[6:7]
	global_load_dword v201, v69, s[6:7] offset:1024
	global_load_dword v202, v69, s[6:7] offset:2048
	s_add_i32 s4, s51, 5
	s_max_i32 s4, s4, 0
	s_add_i32 s4, s4, s95
	s_mul_i32 s4, s4, 0x1a00
	s_add_u32 s6, s48, s4
	s_addc_u32 s7, s49, 0
	global_load_dword v203, v69, s[6:7]
	global_load_dword v204, v69, s[6:7] offset:1024
	global_load_dword v205, v69, s[6:7] offset:2048
	s_add_i32 s4, s51, 6
	s_max_i32 s4, s4, 0
	s_add_i32 s4, s4, s95
	s_mul_i32 s4, s4, 0x1a00
	s_add_u32 s6, s48, s4
	s_addc_u32 s7, s49, 0
	global_load_dword v206, v69, s[6:7]
	global_load_dword v207, v69, s[6:7] offset:1024
	global_load_dword v208, v69, s[6:7] offset:2048
	v_mov_b32_e32 v70, s52
	v_add_u32_e32 v70, 0x10000, v70
	ds_read_b128 v[0:3], v70 offset:6144
	ds_read_b128 v[4:7], v70 offset:6400
	s_waitcnt vmcnt(0)
	v_lshlrev_b32_e32 v88, 16, v188
	v_and_b32_e32 v89, 0xffff0000, v188
	v_lshlrev_b32_e32 v90, 16, v189
	v_and_b32_e32 v91, 0xffff0000, v189
	v_lshlrev_b32_e32 v92, 16, v190
	v_and_b32_e32 v93, 0xffff0000, v190
	v_lshlrev_b32_e32 v94, 16, v191
	v_and_b32_e32 v95, 0xffff0000, v191
	v_lshlrev_b32_e32 v96, 16, v192
	v_and_b32_e32 v97, 0xffff0000, v192
	v_lshlrev_b32_e32 v98, 16, v193
	v_and_b32_e32 v99, 0xffff0000, v193
	v_lshlrev_b32_e32 v100, 16, v194
	v_and_b32_e32 v101, 0xffff0000, v194
	v_lshlrev_b32_e32 v102, 16, v195
	v_and_b32_e32 v103, 0xffff0000, v195
	v_lshlrev_b32_e32 v104, 16, v196
	v_and_b32_e32 v105, 0xffff0000, v196
	v_lshlrev_b32_e32 v106, 16, v197
	v_and_b32_e32 v107, 0xffff0000, v197
	v_lshlrev_b32_e32 v108, 16, v198
	v_and_b32_e32 v109, 0xffff0000, v198
	v_lshlrev_b32_e32 v110, 16, v199
	v_and_b32_e32 v111, 0xffff0000, v199
	v_lshlrev_b32_e32 v112, 16, v200
	v_and_b32_e32 v113, 0xffff0000, v200
	v_lshlrev_b32_e32 v114, 16, v201
	v_and_b32_e32 v115, 0xffff0000, v201
	v_lshlrev_b32_e32 v116, 16, v202
	v_and_b32_e32 v117, 0xffff0000, v202
	v_lshlrev_b32_e32 v118, 16, v203
	v_and_b32_e32 v119, 0xffff0000, v203
	v_lshlrev_b32_e32 v209, 16, v204
	v_and_b32_e32 v210, 0xffff0000, v204
	v_lshlrev_b32_e32 v211, 16, v205
	v_and_b32_e32 v212, 0xffff0000, v205
	v_lshlrev_b32_e32 v213, 16, v206
	v_and_b32_e32 v214, 0xffff0000, v206
	v_lshlrev_b32_e32 v215, 16, v207
	v_and_b32_e32 v216, 0xffff0000, v207
	v_lshlrev_b32_e32 v217, 16, v208
	v_and_b32_e32 v222, 0xffff0000, v208
	s_cmp_ge_i32 s51, 0
	s_cbranch_scc1 .Ldnb_allvalid
	s_cmp_ge_i32 s51, 0
	s_cbranch_scc1 .Ldnb_v0
	v_mov_b32_e32 v88, 0
	v_mov_b32_e32 v89, 0
	v_mov_b32_e32 v90, 0
	v_mov_b32_e32 v91, 0
	v_mov_b32_e32 v92, 0
	v_mov_b32_e32 v93, 0
.Ldnb_v0:
	s_cmp_ge_i32 s51, -1
	s_cbranch_scc1 .Ldnb_v1
	v_mov_b32_e32 v94, 0
	v_mov_b32_e32 v95, 0
	v_mov_b32_e32 v96, 0
	v_mov_b32_e32 v97, 0
	v_mov_b32_e32 v98, 0
	v_mov_b32_e32 v99, 0
.Ldnb_v1:
	s_cmp_ge_i32 s51, -2
	s_cbranch_scc1 .Ldnb_v2
	v_mov_b32_e32 v100, 0
	v_mov_b32_e32 v101, 0
	v_mov_b32_e32 v102, 0
	v_mov_b32_e32 v103, 0
	v_mov_b32_e32 v104, 0
	v_mov_b32_e32 v105, 0
.Ldnb_v2:
	s_cmp_ge_i32 s51, -3
	s_cbranch_scc1 .Ldnb_v3
	v_mov_b32_e32 v106, 0
	v_mov_b32_e32 v107, 0
	v_mov_b32_e32 v108, 0
	v_mov_b32_e32 v109, 0
	v_mov_b32_e32 v110, 0
	v_mov_b32_e32 v111, 0
.Ldnb_v3:
	s_cmp_ge_i32 s51, -4
	s_cbranch_scc1 .Ldnb_v4
	v_mov_b32_e32 v112, 0
	v_mov_b32_e32 v113, 0
	v_mov_b32_e32 v114, 0
	v_mov_b32_e32 v115, 0
	v_mov_b32_e32 v116, 0
	v_mov_b32_e32 v117, 0
.Ldnb_v4:
	s_cmp_ge_i32 s51, -5
	s_cbranch_scc1 .Ldnb_v5
	v_mov_b32_e32 v118, 0
	v_mov_b32_e32 v119, 0
	v_mov_b32_e32 v209, 0
	v_mov_b32_e32 v210, 0
	v_mov_b32_e32 v211, 0
	v_mov_b32_e32 v212, 0
.Ldnb_v5:
	s_cmp_ge_i32 s51, -6
	s_cbranch_scc1 .Ldnb_v6
	v_mov_b32_e32 v213, 0
	v_mov_b32_e32 v214, 0
	v_mov_b32_e32 v215, 0
	v_mov_b32_e32 v216, 0
	v_mov_b32_e32 v217, 0
	v_mov_b32_e32 v222, 0
.Ldnb_v6:
.Ldnb_allvalid:
	v_mul_f32_e32 v223, v8, v88
	v_mul_f32_e32 v224, v9, v89
	v_mul_f32_e32 v225, v16, v90
	v_mul_f32_e32 v226, v17, v91
	v_mul_f32_e32 v227, v24, v92
	v_mul_f32_e32 v228, v25, v93
	v_mul_f32_e32 v229, v8, v94
	v_mul_f32_e32 v230, v9, v95
	v_mul_f32_e32 v231, v16, v96
	v_mul_f32_e32 v232, v17, v97
	v_mul_f32_e32 v233, v24, v98
	v_mul_f32_e32 v234, v25, v99
	v_mul_f32_e32 v235, v8, v100
	v_mul_f32_e32 v236, v9, v101
	v_mul_f32_e32 v237, v16, v102
	v_mul_f32_e32 v238, v17, v103
	v_mul_f32_e32 v239, v24, v104
	v_mul_f32_e32 v240, v25, v105
	v_mul_f32_e32 v241, v8, v106
	v_mul_f32_e32 v242, v9, v107
	v_mul_f32_e32 v243, v16, v108
	v_mul_f32_e32 v244, v17, v109
	v_mul_f32_e32 v245, v24, v110
	v_mul_f32_e32 v246, v25, v111
	v_fmac_f32_e32 v223, v10, v94
	v_fmac_f32_e32 v224, v11, v95
	v_fmac_f32_e32 v225, v18, v96
	v_fmac_f32_e32 v226, v19, v97
	v_fmac_f32_e32 v227, v26, v98
	v_fmac_f32_e32 v228, v27, v99
	v_fmac_f32_e32 v229, v10, v100
	v_fmac_f32_e32 v230, v11, v101
	v_fmac_f32_e32 v231, v18, v102
	v_fmac_f32_e32 v232, v19, v103
	v_fmac_f32_e32 v233, v26, v104
	v_fmac_f32_e32 v234, v27, v105
	v_fmac_f32_e32 v235, v10, v106
	v_fmac_f32_e32 v236, v11, v107
	v_fmac_f32_e32 v237, v18, v108
	v_fmac_f32_e32 v238, v19, v109
	v_fmac_f32_e32 v239, v26, v110
	v_fmac_f32_e32 v240, v27, v111
	v_fmac_f32_e32 v241, v10, v112
	v_fmac_f32_e32 v242, v11, v113
	v_fmac_f32_e32 v243, v18, v114
	v_fmac_f32_e32 v244, v19, v115
	v_fmac_f32_e32 v245, v26, v116
	v_fmac_f32_e32 v246, v27, v117
	v_fmac_f32_e32 v223, v12, v100
	v_fmac_f32_e32 v224, v13, v101
	v_fmac_f32_e32 v225, v20, v102
	v_fmac_f32_e32 v226, v21, v103
	v_fmac_f32_e32 v227, v28, v104
	v_fmac_f32_e32 v228, v29, v105
	v_fmac_f32_e32 v229, v12, v106
	v_fmac_f32_e32 v230, v13, v107
	v_fmac_f32_e32 v231, v20, v108
	v_fmac_f32_e32 v232, v21, v109
	v_fmac_f32_e32 v233, v28, v110
	v_fmac_f32_e32 v234, v29, v111
	v_fmac_f32_e32 v235, v12, v112
	v_fmac_f32_e32 v236, v13, v113
	v_fmac_f32_e32 v237, v20, v114
	v_fmac_f32_e32 v238, v21, v115
	v_fmac_f32_e32 v239, v28, v116
	v_fmac_f32_e32 v240, v29, v117
	v_fmac_f32_e32 v241, v12, v118
	v_fmac_f32_e32 v242, v13, v119
	v_fmac_f32_e32 v243, v20, v209
	v_fmac_f32_e32 v244, v21, v210
	v_fmac_f32_e32 v245, v28, v211
	v_fmac_f32_e32 v246, v29, v212
	v_fmac_f32_e32 v223, v14, v106
	v_fmac_f32_e32 v224, v15, v107
	v_fmac_f32_e32 v225, v22, v108
	v_fmac_f32_e32 v226, v23, v109
	v_fmac_f32_e32 v227, v30, v110
	v_fmac_f32_e32 v228, v31, v111
	v_fmac_f32_e32 v229, v14, v112
	v_fmac_f32_e32 v230, v15, v113
	v_fmac_f32_e32 v231, v22, v114
	v_fmac_f32_e32 v232, v23, v115
	v_fmac_f32_e32 v233, v30, v116
	v_fmac_f32_e32 v234, v31, v117
	v_fmac_f32_e32 v235, v14, v118
	v_fmac_f32_e32 v236, v15, v119
	v_fmac_f32_e32 v237, v22, v209
	v_fmac_f32_e32 v238, v23, v210
	v_fmac_f32_e32 v239, v30, v211
	v_fmac_f32_e32 v240, v31, v212
	v_fmac_f32_e32 v241, v14, v213
	v_fmac_f32_e32 v242, v15, v214
	v_fmac_f32_e32 v243, v22, v215
	v_fmac_f32_e32 v244, v23, v216
	v_fmac_f32_e32 v245, v30, v217
	v_fmac_f32_e32 v246, v31, v222
	v_mul_f32_e64 v88, -v223, s54
	v_mul_f32_e64 v89, -v224, s54
	v_mul_f32_e64 v90, -v225, s54
	v_mul_f32_e64 v91, -v226, s54
	v_mul_f32_e64 v92, -v227, s54
	v_mul_f32_e64 v93, -v228, s54
	v_mul_f32_e64 v94, -v229, s54
	v_mul_f32_e64 v95, -v230, s54
	v_mul_f32_e64 v96, -v231, s54
	v_mul_f32_e64 v97, -v232, s54
	v_mul_f32_e64 v98, -v233, s54
	v_mul_f32_e64 v99, -v234, s54
	v_mul_f32_e64 v100, -v235, s54
	v_mul_f32_e64 v101, -v236, s54
	v_mul_f32_e64 v102, -v237, s54
	v_mul_f32_e64 v103, -v238, s54
	v_mul_f32_e64 v104, -v239, s54
	v_mul_f32_e64 v105, -v240, s54
	v_mul_f32_e64 v106, -v241, s54
	v_mul_f32_e64 v107, -v242, s54
	v_mul_f32_e64 v108, -v243, s54
	v_mul_f32_e64 v109, -v244, s54
	v_mul_f32_e64 v110, -v245, s54
	v_mul_f32_e64 v111, -v246, s54
	v_exp_f32_e32 v88, v88
	v_exp_f32_e32 v89, v89
	v_exp_f32_e32 v90, v90
	v_exp_f32_e32 v91, v91
	v_exp_f32_e32 v92, v92
	v_exp_f32_e32 v93, v93
	v_exp_f32_e32 v94, v94
	v_exp_f32_e32 v95, v95
	v_exp_f32_e32 v96, v96
	v_exp_f32_e32 v97, v97
	v_exp_f32_e32 v98, v98
	v_exp_f32_e32 v99, v99
	v_exp_f32_e32 v100, v100
	v_exp_f32_e32 v101, v101
	v_exp_f32_e32 v102, v102
	v_exp_f32_e32 v103, v103
	v_exp_f32_e32 v104, v104
	v_exp_f32_e32 v105, v105
	v_exp_f32_e32 v106, v106
	v_exp_f32_e32 v107, v107
	v_exp_f32_e32 v108, v108
	v_exp_f32_e32 v109, v109
	v_exp_f32_e32 v110, v110
	v_exp_f32_e32 v111, v111
	v_add_f32_e32 v88, 1.0, v88
	v_add_f32_e32 v89, 1.0, v89
	v_add_f32_e32 v90, 1.0, v90
	v_add_f32_e32 v91, 1.0, v91
	v_add_f32_e32 v92, 1.0, v92
	v_add_f32_e32 v93, 1.0, v93
	v_add_f32_e32 v94, 1.0, v94
	v_add_f32_e32 v95, 1.0, v95
	v_add_f32_e32 v96, 1.0, v96
	v_add_f32_e32 v97, 1.0, v97
	v_add_f32_e32 v98, 1.0, v98
	v_add_f32_e32 v99, 1.0, v99
	v_add_f32_e32 v100, 1.0, v100
	v_add_f32_e32 v101, 1.0, v101
	v_add_f32_e32 v102, 1.0, v102
	v_add_f32_e32 v103, 1.0, v103
	v_add_f32_e32 v104, 1.0, v104
	v_add_f32_e32 v105, 1.0, v105
	v_add_f32_e32 v106, 1.0, v106
	v_add_f32_e32 v107, 1.0, v107
	v_add_f32_e32 v108, 1.0, v108
	v_add_f32_e32 v109, 1.0, v109
	v_add_f32_e32 v110, 1.0, v110
	v_add_f32_e32 v111, 1.0, v111
	v_rcp_f32_e32 v88, v88
	v_rcp_f32_e32 v89, v89
	v_rcp_f32_e32 v90, v90
	v_rcp_f32_e32 v91, v91
	v_rcp_f32_e32 v92, v92
	v_rcp_f32_e32 v93, v93
	v_rcp_f32_e32 v94, v94
	v_rcp_f32_e32 v95, v95
	v_rcp_f32_e32 v96, v96
	v_rcp_f32_e32 v97, v97
	v_rcp_f32_e32 v98, v98
	v_rcp_f32_e32 v99, v99
	v_rcp_f32_e32 v100, v100
	v_rcp_f32_e32 v101, v101
	v_rcp_f32_e32 v102, v102
	v_rcp_f32_e32 v103, v103
	v_rcp_f32_e32 v104, v104
	v_rcp_f32_e32 v105, v105
	v_rcp_f32_e32 v106, v106
	v_rcp_f32_e32 v107, v107
	v_rcp_f32_e32 v108, v108
	v_rcp_f32_e32 v109, v109
	v_rcp_f32_e32 v110, v110
	v_rcp_f32_e32 v111, v111
	v_mul_f32_e32 v223, v223, v88
	v_mul_f32_e32 v224, v224, v89
	v_mul_f32_e32 v225, v225, v90
	v_mul_f32_e32 v226, v226, v91
	v_mul_f32_e32 v227, v227, v92
	v_mul_f32_e32 v228, v228, v93
	v_mul_f32_e32 v229, v229, v94
	v_mul_f32_e32 v230, v230, v95
	v_mul_f32_e32 v231, v231, v96
	v_mul_f32_e32 v232, v232, v97
	v_mul_f32_e32 v233, v233, v98
	v_mul_f32_e32 v234, v234, v99
	v_mul_f32_e32 v235, v235, v100
	v_mul_f32_e32 v236, v236, v101
	v_mul_f32_e32 v237, v237, v102
	v_mul_f32_e32 v238, v238, v103
	v_mul_f32_e32 v239, v239, v104
	v_mul_f32_e32 v240, v240, v105
	v_mul_f32_e32 v241, v241, v106
	v_mul_f32_e32 v242, v242, v107
	v_mul_f32_e32 v243, v243, v108
	v_mul_f32_e32 v244, v244, v109
	v_mul_f32_e32 v245, v245, v110
	v_mul_f32_e32 v246, v246, v111
	v_mul_f32_e32 v112, v223, v223
	v_mul_f32_e32 v113, v225, v225
	v_mul_f32_e32 v114, v229, v229
	v_mul_f32_e32 v115, v231, v231
	v_mul_f32_e32 v116, v235, v235
	v_mul_f32_e32 v117, v237, v237
	v_mul_f32_e32 v118, v241, v241
	v_mul_f32_e32 v119, v243, v243
	v_fmac_f32_e32 v112, v224, v224
	v_fmac_f32_e32 v113, v226, v226
	v_fmac_f32_e32 v114, v230, v230
	v_fmac_f32_e32 v115, v232, v232
	v_fmac_f32_e32 v116, v236, v236
	v_fmac_f32_e32 v117, v238, v238
	v_fmac_f32_e32 v118, v242, v242
	v_fmac_f32_e32 v119, v244, v244
	v_add_f32_dpp v112, v112, v112 row_ror:8 row_mask:0xf bank_mask:0xf
	v_add_f32_dpp v113, v113, v113 row_ror:8 row_mask:0xf bank_mask:0xf
	v_add_f32_dpp v114, v114, v114 row_ror:8 row_mask:0xf bank_mask:0xf
	v_add_f32_dpp v115, v115, v115 row_ror:8 row_mask:0xf bank_mask:0xf
	v_add_f32_dpp v116, v116, v116 row_ror:8 row_mask:0xf bank_mask:0xf
	v_add_f32_dpp v117, v117, v117 row_ror:8 row_mask:0xf bank_mask:0xf
	v_add_f32_dpp v118, v118, v118 row_ror:8 row_mask:0xf bank_mask:0xf
	v_add_f32_dpp v119, v119, v119 row_ror:8 row_mask:0xf bank_mask:0xf
	v_add_f32_dpp v112, v112, v112 row_ror:4 row_mask:0xf bank_mask:0xf
	v_add_f32_dpp v113, v113, v113 row_ror:4 row_mask:0xf bank_mask:0xf
	v_add_f32_dpp v114, v114, v114 row_ror:4 row_mask:0xf bank_mask:0xf
	v_add_f32_dpp v115, v115, v115 row_ror:4 row_mask:0xf bank_mask:0xf
	v_add_f32_dpp v116, v116, v116 row_ror:4 row_mask:0xf bank_mask:0xf
	v_add_f32_dpp v117, v117, v117 row_ror:4 row_mask:0xf bank_mask:0xf
	v_add_f32_dpp v118, v118, v118 row_ror:4 row_mask:0xf bank_mask:0xf
	v_add_f32_dpp v119, v119, v119 row_ror:4 row_mask:0xf bank_mask:0xf
	v_add_f32_dpp v112, v112, v112 row_ror:2 row_mask:0xf bank_mask:0xf
	v_add_f32_dpp v113, v113, v113 row_ror:2 row_mask:0xf bank_mask:0xf
	v_add_f32_dpp v114, v114, v114 row_ror:2 row_mask:0xf bank_mask:0xf
	v_add_f32_dpp v115, v115, v115 row_ror:2 row_mask:0xf bank_mask:0xf
	v_add_f32_dpp v116, v116, v116 row_ror:2 row_mask:0xf bank_mask:0xf
	v_add_f32_dpp v117, v117, v117 row_ror:2 row_mask:0xf bank_mask:0xf
	v_add_f32_dpp v118, v118, v118 row_ror:2 row_mask:0xf bank_mask:0xf
	v_add_f32_dpp v119, v119, v119 row_ror:2 row_mask:0xf bank_mask:0xf
	v_add_f32_dpp v112, v112, v112 row_ror:1 row_mask:0xf bank_mask:0xf
	v_add_f32_dpp v113, v113, v113 row_ror:1 row_mask:0xf bank_mask:0xf
	v_add_f32_dpp v114, v114, v114 row_ror:1 row_mask:0xf bank_mask:0xf
	v_add_f32_dpp v115, v115, v115 row_ror:1 row_mask:0xf bank_mask:0xf
	v_add_f32_dpp v116, v116, v116 row_ror:1 row_mask:0xf bank_mask:0xf
	v_add_f32_dpp v117, v117, v117 row_ror:1 row_mask:0xf bank_mask:0xf
	v_add_f32_dpp v118, v118, v118 row_ror:1 row_mask:0xf bank_mask:0xf
	v_add_f32_dpp v119, v119, v119 row_ror:1 row_mask:0xf bank_mask:0xf
	s_nop 0
	ds_bpermute_b32 v209, v57, v112
	ds_bpermute_b32 v210, v57, v113
	ds_bpermute_b32 v211, v57, v114
	ds_bpermute_b32 v212, v57, v115
	ds_bpermute_b32 v213, v57, v116
	ds_bpermute_b32 v214, v57, v117
	ds_bpermute_b32 v215, v57, v118
	ds_bpermute_b32 v216, v57, v119
	s_waitcnt lgkmcnt(0)
	v_add_f32_e32 v112, v112, v209
	v_add_f32_e32 v113, v113, v210
	v_add_f32_e32 v114, v114, v211
	v_add_f32_e32 v115, v115, v212
	v_add_f32_e32 v116, v116, v213
	v_add_f32_e32 v117, v117, v214
	v_add_f32_e32 v118, v118, v215
	v_add_f32_e32 v119, v119, v216
	s_nop 0
	ds_bpermute_b32 v209, v56, v112
	ds_bpermute_b32 v210, v56, v113
	ds_bpermute_b32 v211, v56, v114
	ds_bpermute_b32 v212, v56, v115
	ds_bpermute_b32 v213, v56, v116
	ds_bpermute_b32 v214, v56, v117
	ds_bpermute_b32 v215, v56, v118
	ds_bpermute_b32 v216, v56, v119
	s_waitcnt lgkmcnt(0)
	v_add_f32_e32 v112, v112, v209
	v_add_f32_e32 v113, v113, v210
	v_add_f32_e32 v114, v114, v211
	v_add_f32_e32 v115, v115, v212
	v_add_f32_e32 v116, v116, v213
	v_add_f32_e32 v117, v117, v214
	v_add_f32_e32 v118, v118, v215
	v_add_f32_e32 v119, v119, v216
	v_add_f32_e32 v112, 0x358637bd, v112
	v_add_f32_e32 v113, 0x358637bd, v113
	v_add_f32_e32 v114, 0x358637bd, v114
	v_add_f32_e32 v115, 0x358637bd, v115
	v_add_f32_e32 v116, 0x358637bd, v116
	v_add_f32_e32 v117, 0x358637bd, v117
	v_add_f32_e32 v118, 0x358637bd, v118
	v_add_f32_e32 v119, 0x358637bd, v119
	v_rsq_f32_e32 v112, v112
	v_rsq_f32_e32 v113, v113
	v_rsq_f32_e32 v114, v114
	v_rsq_f32_e32 v115, v115
	v_rsq_f32_e32 v116, v116
	v_rsq_f32_e32 v117, v117
	v_rsq_f32_e32 v118, v118
	v_rsq_f32_e32 v119, v119
	v_mul_f32_e32 v209, 0x3fb8aa3b, v0
	v_mul_f32_e32 v210, 0x3fb8aa3b, v1
	v_mul_f32_e32 v211, 0x3fb8aa3b, v2
	v_mul_f32_e32 v212, 0x3fb8aa3b, v3
	v_exp_f32_e32 v209, v209
	v_exp_f32_e32 v210, v210
	v_exp_f32_e32 v211, v211
	v_exp_f32_e32 v212, v212
	v_mul_f32_e32 v112, 0x3db504f3, v112
	v_mul_f32_e32 v114, 0x3db504f3, v114
	v_mul_f32_e32 v116, 0x3db504f3, v116
	v_mul_f32_e32 v118, 0x3db504f3, v118
	v_mul_f32_e32 v213, v4, v209
	v_mul_f32_e32 v214, v5, v210
	v_mul_f32_e32 v215, v6, v211
	v_mul_f32_e32 v216, v7, v212
	v_mul_f32_e32 v223, v223, v112
	v_mul_f32_e32 v225, v225, v113
	v_mul_f32_e32 v227, v227, v4
	v_mul_f32_e32 v224, v224, v112
	v_mul_f32_e32 v226, v226, v113
	v_mul_f32_e32 v228, v228, v4
	v_mul_f32_e32 v229, v229, v114
	v_mul_f32_e32 v231, v231, v115
	v_mul_f32_e32 v233, v233, v5
	v_mul_f32_e32 v230, v230, v114
	v_mul_f32_e32 v232, v232, v115
	v_mul_f32_e32 v234, v234, v5
	v_mul_f32_e32 v235, v235, v116
	v_mul_f32_e32 v237, v237, v117
	v_mul_f32_e32 v239, v239, v6
	v_mul_f32_e32 v236, v236, v116
	v_mul_f32_e32 v238, v238, v117
	v_mul_f32_e32 v240, v240, v6
	v_mul_f32_e32 v241, v241, v118
	v_mul_f32_e32 v243, v243, v119
	v_mul_f32_e32 v245, v245, v7
	v_mul_f32_e32 v242, v242, v118
	v_mul_f32_e32 v244, v244, v119
	v_mul_f32_e32 v246, v246, v7
	v_cvt_pk_bf16_f32 v42, v223, v224
	v_cvt_pk_bf16_f32 v43, v225, v226
	v_mul_f32_e32 v49, v223, v209
	v_mul_f32_e32 v50, v224, v209
	ds_write_b32 v63, v42
	ds_write_b32 v63, v43 offset:17408
	v_cvt_pk_bf16_f32 v48, v49, v50
	v_mul_f32_e32 v225, v225, v213
	v_mul_f32_e32 v226, v226, v213
	global_store_dword v[40:41], v48, off offset:-512
	v_cvt_pk_bf16_f32 v42, v229, v230
	v_cvt_pk_bf16_f32 v43, v231, v232
	v_mul_f32_e32 v49, v229, v210
	v_mul_f32_e32 v50, v230, v210
	ds_write_b32 v63, v42 offset:272
	ds_write_b32 v63, v43 offset:17680
	v_cvt_pk_bf16_f32 v48, v49, v50
	v_mul_f32_e32 v231, v231, v214
	v_mul_f32_e32 v232, v232, v214
	global_store_dword v[40:41], v48, off offset:-256
	v_cvt_pk_bf16_f32 v42, v235, v236
	v_cvt_pk_bf16_f32 v43, v237, v238
	v_mul_f32_e32 v49, v235, v211
	v_mul_f32_e32 v50, v236, v211
	ds_write_b32 v63, v42 offset:544
	ds_write_b32 v63, v43 offset:17952
	v_cvt_pk_bf16_f32 v48, v49, v50
	v_mul_f32_e32 v237, v237, v215
	v_mul_f32_e32 v238, v238, v215
	global_store_dword v[40:41], v48, off
	v_cvt_pk_bf16_f32 v42, v241, v242
	v_cvt_pk_bf16_f32 v43, v243, v244
	v_mul_f32_e32 v49, v241, v212
	v_mul_f32_e32 v50, v242, v212
	ds_write_b32 v63, v42 offset:816
	ds_write_b32 v63, v43 offset:18224
	v_cvt_pk_bf16_f32 v48, v49, v50
	v_mul_f32_e32 v243, v243, v216
	v_mul_f32_e32 v244, v244, v216
	global_store_dword v[40:41], v48, off offset:256
	v_cvt_pk_bf16_f32 v44, v225, v231
	v_cvt_pk_bf16_f32 v45, v237, v243
	v_cvt_pk_bf16_f32 v46, v226, v232
	v_cvt_pk_bf16_f32 v47, v238, v244
	ds_write_b64 v71, v[44:45]
	ds_write_b64 v71, v[46:47] offset:144
	v_cvt_pk_bf16_f32 v44, v227, v233
	v_cvt_pk_bf16_f32 v45, v239, v245
	v_cvt_pk_bf16_f32 v46, v228, v234
	v_cvt_pk_bf16_f32 v47, v240, v246
	ds_write_b64 v71, v[44:45] offset:18432
	ds_write_b64 v71, v[46:47] offset:18576
	v_add_u32_e32 v63, 0x440, v63
	v_add_u32_e32 v71, 8, v71
	v_lshl_add_u64 v[40:41], v[40:41], 0, s[0:1]
	s_add_i32 s51, s51, 4
	s_add_i32 s52, s52, 16
	s_add_i32 s53, s53, 1
	s_cmp_lt_u32 s53, 4
	s_cbranch_scc1 .Ldnb_group
	v_lshrrev_b32_e32 v38, 5, v33
	v_ashrrev_i32_e32 v37, 2, v35
	s_movk_i32 s0, 0xffe0
	v_bfi_b32 v0, s0, v37, v35
	v_lshlrev_b32_e32 v4, 4, v38
	v_mad_u64_u32 v[48:49], s[0:1], v0, s94, v[4:5]
	s_waitcnt lgkmcnt(0)
	s_barrier
	ds_read_b128 v[0:3], v48 offset:17408
	v_and_b32_e32 v36, 31, v35
	v_and_or_b32 v39, v34, 32, v36
	v_mad_u32_u24 v49, v39, s94, v4
	ds_read_b128 v[4:7], v49 offset:17408
	s_waitcnt lgkmcnt(0)
	v_mfma_f32_32x32x16_bf16 v[16:31], v[0:3], v[4:7], 0
	ds_read_b128 v[0:3], v48
	ds_read_b128 v[40:43], v48 offset:17440
	ds_read_b128 v[44:47], v49 offset:17440
	v_and_b32_e32 v52, 0xffffffe0, v37
	v_lshl_or_b32 v37, v39, 2, v85
	s_waitcnt lgkmcnt(0)
	v_mfma_f32_32x32x16_bf16 v[16:31], v[40:43], v[44:47], v[16:31]
	ds_read_b128 v[40:43], v48 offset:32
	v_mfma_f32_32x32x16_bf16 v[0:15], v[0:3], v[4:7], 0
	s_waitcnt lgkmcnt(0)
	v_mfma_f32_32x32x16_bf16 v[0:15], v[40:43], v[44:47], v[0:15]
	ds_read_b128 v[40:43], v48 offset:17472
	ds_read_b128 v[44:47], v49 offset:17472
	s_waitcnt lgkmcnt(0)
	v_mfma_f32_32x32x16_bf16 v[16:31], v[40:43], v[44:47], v[16:31]
	ds_read_b128 v[40:43], v48 offset:64
	s_waitcnt lgkmcnt(0)
	v_mfma_f32_32x32x16_bf16 v[0:15], v[40:43], v[44:47], v[0:15]
	ds_read_b128 v[40:43], v48 offset:17504
	ds_read_b128 v[44:47], v49 offset:17504
	s_waitcnt lgkmcnt(0)
	v_mfma_f32_32x32x16_bf16 v[16:31], v[40:43], v[44:47], v[16:31]
	ds_read_b128 v[40:43], v48 offset:96
	s_waitcnt lgkmcnt(0)
	v_mfma_f32_32x32x16_bf16 v[0:15], v[40:43], v[44:47], v[0:15]
	ds_read_b128 v[40:43], v48 offset:17536
	ds_read_b128 v[44:47], v49 offset:17536
	s_waitcnt lgkmcnt(0)
	v_mfma_f32_32x32x16_bf16 v[16:31], v[40:43], v[44:47], v[16:31]
	ds_read_b128 v[40:43], v48 offset:128
	s_waitcnt lgkmcnt(0)
	v_mfma_f32_32x32x16_bf16 v[0:15], v[40:43], v[44:47], v[0:15]
	ds_read_b128 v[40:43], v48 offset:17568
	ds_read_b128 v[44:47], v49 offset:17568
	s_waitcnt lgkmcnt(0)
	v_mfma_f32_32x32x16_bf16 v[16:31], v[40:43], v[44:47], v[16:31]
	ds_read_b128 v[40:43], v48 offset:160
	s_waitcnt lgkmcnt(0)
	v_mfma_f32_32x32x16_bf16 v[0:15], v[40:43], v[44:47], v[0:15]
	ds_read_b128 v[40:43], v48 offset:17600
	ds_read_b128 v[44:47], v49 offset:17600
	s_waitcnt lgkmcnt(0)
	v_mfma_f32_32x32x16_bf16 v[16:31], v[40:43], v[44:47], v[16:31]
	ds_read_b128 v[40:43], v48 offset:192
	s_waitcnt lgkmcnt(0)
	v_mfma_f32_32x32x16_bf16 v[0:15], v[40:43], v[44:47], v[0:15]
	ds_read_b128 v[40:43], v48 offset:17632
	ds_read_b128 v[44:47], v49 offset:17632
	ds_read_b128 v[48:51], v48 offset:224
	s_waitcnt lgkmcnt(0)
	s_barrier
	v_mfma_f32_32x32x16_bf16 v[16:31], v[40:43], v[44:47], v[16:31]
	ds_read_b32 v40, v37
	v_lshlrev_b32_e32 v37, 2, v38
	v_or_b32_e32 v41, v37, v52
	v_cmp_ge_i32_e32 vcc, v41, v39
	v_mov_b32_e32 v42, 0
	v_mov_b32_e32 v43, 0
	v_mfma_f32_32x32x16_bf16 v[0:15], v[48:51], v[44:47], v[0:15]
	s_and_saveexec_b64 s[4:5], vcc
	s_cbranch_execz .LBB0_216
	v_lshl_add_u32 v43, v41, 2, v85
	ds_read_b32 v43, v43
	s_waitcnt lgkmcnt(0)
	v_sub_f32_e32 v43, v43, v40
	v_mul_f32_e32 v44, 0x3fb8aa3b, v43
	v_fma_f32 v45, v43, s33, -v44
	v_rndne_f32_e32 v46, v44
	v_fmac_f32_e32 v45, 0x32a5705f, v43
	v_sub_f32_e32 v44, v44, v46
	v_add_f32_e32 v44, v44, v45
	v_cvt_i32_f32_e32 v46, v46
	v_exp_f32_e32 v44, v44
	v_cmp_ngt_f32_e64 s[0:1], s79, v43
	v_ldexp_f32 v44, v44, v46
	s_nop 0
	v_cndmask_b32_e64 v44, 0, v44, s[0:1]
	v_cmp_nlt_f32_e64 s[0:1], s82, v43
	s_nop 1
	v_cndmask_b32_e64 v43, v73, v44, s[0:1]

.LBB0_2000:
	s_or_b64 exec, exec, s[12:13]
	s_ashr_i32 s1, s0, 31
	s_lshl_b64 s[12:13], s[0:1], 13
	s_lshl_b64 s[14:15], s[0:1], 14
	s_waitcnt vmcnt(4)
	v_ashrrev_i32_e32 v6, 6, v0
	s_add_u32 s14, s6, s14
	s_addc_u32 s15, s7, s15
	v_add_u32_e32 v1, s19, v6
	s_lshl_b32 s19, s33, 1
	v_readlane_b32 s40, v252, 37
	s_waitcnt vmcnt(3)
	v_and_b32_e32 v7, 63, v0
	v_readlane_b32 s41, v252, 38
	s_add_u32 s40, s40, s19
	s_addc_u32 s41, s41, 0
	s_waitcnt vmcnt(0)
	v_lshlrev_b32_e32 v16, 2, v7
	v_max_i32_e32 v4, 0, v1
	v_lshl_add_u64 v[2:3], s[40:41], 0, v[16:17]
	v_add_u32_e32 v4, s17, v4
	v_max_i32_e32 v8, -4, v1
	v_max_i32_e32 v10, -8, v1
	v_max_i32_e32 v13, -12, v1
	v_mad_i64_i32 v[4:5], s[40:41], v4, s29, v[2:3]
	v_add3_u32 v8, v8, s17, 4
	v_add3_u32 v10, v10, s17, 8
	v_add3_u32 v13, v13, s17, 12
	s_waitcnt lgkmcnt(0)
	s_barrier
	v_mad_i64_i32 v[8:9], s[40:41], v8, s29, v[2:3]
	v_mad_i64_i32 v[10:11], s[40:41], v10, s29, v[2:3]
	v_mad_i64_i32 v[14:15], s[40:41], v13, s29, v[2:3]
	global_load_dword v42, v[4:5], off
	global_load_dword v43, v[4:5], off offset:1024
	global_load_dword v44, v[8:9], off
	global_load_dword v45, v[8:9], off offset:1024
	global_load_dword v46, v[10:11], off
	global_load_dword v47, v[10:11], off offset:1024
	global_load_dword v48, v[14:15], off
	global_load_dword v49, v[14:15], off offset:1024
	v_max_i32_e32 v4, -16, v1
	v_add3_u32 v4, s17, 16, v4
	v_max_i32_e32 v8, 0xffffffec, v1
	v_max_i32_e32 v10, 0xffffffe8, v1
	v_max_i32_e32 v13, 0xffffffe4, v1
	v_mad_i64_i32 v[4:5], s[40:41], v4, s29, v[2:3]
	v_add3_u32 v8, s17, 20, v8
	v_add3_u32 v10, s17, 24, v10
	v_add3_u32 v13, s17, 28, v13
	v_mad_i64_i32 v[8:9], s[40:41], v8, s29, v[2:3]
	v_mad_i64_i32 v[10:11], s[40:41], v10, s29, v[2:3]
	v_mad_i64_i32 v[14:15], s[40:41], v13, s29, v[2:3]
	global_load_dword v50, v[4:5], off
	global_load_dword v37, v[4:5], off offset:1024
	global_load_dword v36, v[8:9], off
	global_load_dword v35, v[8:9], off offset:1024
	global_load_dword v34, v[10:11], off
	global_load_dword v33, v[10:11], off offset:1024
	global_load_dword v32, v[14:15], off
	global_load_dword v31, v[14:15], off offset:1024
	v_max_i32_e32 v4, 0xffffffe0, v1
	v_add3_u32 v4, s17, 32, v4
	v_max_i32_e32 v8, 0xffffffdc, v1
	v_max_i32_e32 v10, 0xffffffd8, v1
	v_max_i32_e32 v13, 0xffffffd4, v1
	v_mad_i64_i32 v[4:5], s[40:41], v4, s29, v[2:3]
	v_add3_u32 v8, s17, 36, v8
	v_add3_u32 v10, s17, 40, v10
	v_add3_u32 v13, s17, 44, v13
	v_mad_i64_i32 v[8:9], s[40:41], v8, s29, v[2:3]
	v_mad_i64_i32 v[10:11], s[40:41], v10, s29, v[2:3]
	v_mad_i64_i32 v[14:15], s[40:41], v13, s29, v[2:3]
	global_load_dword v30, v[4:5], off
	global_load_dword v29, v[4:5], off offset:1024
	global_load_dword v28, v[8:9], off
	global_load_dword v27, v[8:9], off offset:1024
	global_load_dword v26, v[10:11], off
	global_load_dword v25, v[10:11], off offset:1024
	global_load_dword v24, v[14:15], off
	global_load_dword v23, v[14:15], off offset:1024
	v_add_u32_e32 v4, s18, v6
	v_max_i32_e32 v4, 0, v4
	v_max_i32_e32 v8, 0xffffffcc, v1
	v_add_u32_e32 v4, s17, v4
	v_add3_u32 v8, s17, 52, v8
	v_max_i32_e32 v10, 0xffffffc8, v1
	v_max_i32_e32 v1, 0xffffffc4, v1
	v_mad_i64_i32 v[4:5], s[18:19], v4, s29, v[2:3]
	v_mad_i64_i32 v[8:9], s[18:19], v8, s29, v[2:3]
	v_add3_u32 v10, s17, 56, v10
	v_add3_u32 v1, s17, 60, v1
	v_mad_i64_i32 v[38:39], s[18:19], v10, s29, v[2:3]
	v_mad_i64_i32 v[2:3], s[18:19], v1, s29, v[2:3]
	global_load_dword v19, v[4:5], off
	global_load_dword v15, v[4:5], off offset:1024
	global_load_dword v14, v[8:9], off
	global_load_dword v13, v[8:9], off offset:1024
	global_load_dword v11, v[38:39], off
	global_load_dword v10, v[38:39], off offset:1024
	s_nop 0
	global_load_dword v8, v[2:3], off
	global_load_dword v1, v[2:3], off offset:1024
	v_and_b32_e32 v2, 63, v0
	v_lshrrev_b32_e32 v3, 6, v0
	v_lshlrev_b32_e32 v4, 9, v3
	v_lshl_or_b32 v4, v2, 3, v4
	v_mul_u32_u24_e32 v5, 0x110, v3
	v_lshl_add_u32 v5, v2, 2, v5
	v_lshlrev_b32_e32 v9, 8, v3
	v_lshl_or_b32 v9, v2, 2, v9
	v_add_u32_e32 v16, 0xd600, v5
	ds_read_b64 v[52:53], v4 offset:4096
	v_add_u32_e32 v51, 0, v3
	v_cmp_lt_i32_e32 vcc, s16, v51
	s_waitcnt vmcnt(30) lgkmcnt(0)
	v_mul_f32_e32 v38, 0x3fb8aa3b, v52
	v_mul_f32_e32 v39, 0x3fb8aa3b, v53
	v_mul_f32_e32 v52, 0xbfb8aa3b, v52
	v_mul_f32_e32 v53, 0xbfb8aa3b, v53
	v_exp_f32_e32 v38, v38
	v_exp_f32_e32 v39, v39
	v_exp_f32_e32 v52, v52
	v_exp_f32_e32 v53, v53
	v_lshlrev_b32_e32 v2, 16, v42
	v_and_b32_e32 v42, 0xffff0000, v42
	v_lshlrev_b32_e32 v51, 16, v43
	v_and_b32_e32 v43, 0xffff0000, v43
	v_mul_f32_e32 v2, 0x3db504f3, v2
	v_mul_f32_e32 v42, 0x3db504f3, v42
	v_mul_f32_e32 v2, v2, v38
	v_mul_f32_e32 v42, v42, v39
	v_mul_f32_e32 v51, v51, v52
	v_mul_f32_e32 v43, v43, v53
	v_cndmask_b32_e32 v2, 0, v2, vcc
	v_cndmask_b32_e32 v42, 0, v42, vcc
	v_cndmask_b32_e32 v51, 0, v51, vcc
	v_cndmask_b32_e32 v43, 0, v43, vcc
	v_cvt_pk_bf16_f32 v2, v2, v42
	v_cvt_pk_bf16_f32 v51, v51, v43
	ds_write_b32 v5, v2 offset:37376
	global_store_dword v9, v2, s[14:15]
	ds_write_b32 v16, v51 offset:0
	ds_read_b64 v[52:53], v4 offset:6144
	v_add_u32_e32 v51, 4, v3
	v_cmp_lt_i32_e32 vcc, s16, v51
	s_waitcnt vmcnt(29) lgkmcnt(0)
	v_mul_f32_e32 v38, 0x3fb8aa3b, v52
	v_mul_f32_e32 v39, 0x3fb8aa3b, v53
	v_mul_f32_e32 v52, 0xbfb8aa3b, v52
	v_mul_f32_e32 v53, 0xbfb8aa3b, v53
	v_exp_f32_e32 v38, v38
	v_exp_f32_e32 v39, v39
	v_exp_f32_e32 v52, v52
	v_exp_f32_e32 v53, v53
	v_lshlrev_b32_e32 v2, 16, v44
	v_and_b32_e32 v44, 0xffff0000, v44
	v_lshlrev_b32_e32 v51, 16, v45
	v_and_b32_e32 v45, 0xffff0000, v45
	v_mul_f32_e32 v2, 0x3db504f3, v2
	v_mul_f32_e32 v44, 0x3db504f3, v44
	v_mul_f32_e32 v2, v2, v38
	v_mul_f32_e32 v44, v44, v39
	v_mul_f32_e32 v51, v51, v52
	v_mul_f32_e32 v45, v45, v53
	v_cndmask_b32_e32 v2, 0, v2, vcc
	v_cndmask_b32_e32 v44, 0, v44, vcc
	v_cndmask_b32_e32 v51, 0, v51, vcc
	v_cndmask_b32_e32 v45, 0, v45, vcc
	v_cvt_pk_bf16_f32 v2, v2, v44
	v_cvt_pk_bf16_f32 v51, v51, v45
	ds_write_b32 v5, v2 offset:38464
	global_store_dword v9, v2, s[14:15] offset:1024
	ds_write_b32 v16, v51 offset:1088
	ds_read_b64 v[52:53], v4 offset:8192
	v_add_u32_e32 v51, 8, v3
	v_cmp_lt_i32_e32 vcc, s16, v51
	s_waitcnt vmcnt(28) lgkmcnt(0)
	v_mul_f32_e32 v38, 0x3fb8aa3b, v52
	v_mul_f32_e32 v39, 0x3fb8aa3b, v53
	v_mul_f32_e32 v52, 0xbfb8aa3b, v52
	v_mul_f32_e32 v53, 0xbfb8aa3b, v53
	v_exp_f32_e32 v38, v38
	v_exp_f32_e32 v39, v39
	v_exp_f32_e32 v52, v52
	v_exp_f32_e32 v53, v53
	v_lshlrev_b32_e32 v2, 16, v46
	v_and_b32_e32 v46, 0xffff0000, v46
	v_lshlrev_b32_e32 v51, 16, v47
	v_and_b32_e32 v47, 0xffff0000, v47
	v_mul_f32_e32 v2, 0x3db504f3, v2
	v_mul_f32_e32 v46, 0x3db504f3, v46
	v_mul_f32_e32 v2, v2, v38
	v_mul_f32_e32 v46, v46, v39
	v_mul_f32_e32 v51, v51, v52
	v_mul_f32_e32 v47, v47, v53
	v_cndmask_b32_e32 v2, 0, v2, vcc
	v_cndmask_b32_e32 v46, 0, v46, vcc
	v_cndmask_b32_e32 v51, 0, v51, vcc
	v_cndmask_b32_e32 v47, 0, v47, vcc
	v_cvt_pk_bf16_f32 v2, v2, v46
	v_cvt_pk_bf16_f32 v51, v51, v47
	ds_write_b32 v5, v2 offset:39552
	global_store_dword v9, v2, s[14:15] offset:2048
	ds_write_b32 v16, v51 offset:2176
	ds_read_b64 v[52:53], v4 offset:10240
	v_add_u32_e32 v51, 12, v3
	v_cmp_lt_i32_e32 vcc, s16, v51
	s_waitcnt vmcnt(27) lgkmcnt(0)
	v_mul_f32_e32 v38, 0x3fb8aa3b, v52
	v_mul_f32_e32 v39, 0x3fb8aa3b, v53
	v_mul_f32_e32 v52, 0xbfb8aa3b, v52
	v_mul_f32_e32 v53, 0xbfb8aa3b, v53
	v_exp_f32_e32 v38, v38
	v_exp_f32_e32 v39, v39
	v_exp_f32_e32 v52, v52
	v_exp_f32_e32 v53, v53
	v_lshlrev_b32_e32 v2, 16, v48
	v_and_b32_e32 v48, 0xffff0000, v48
	v_lshlrev_b32_e32 v51, 16, v49
	v_and_b32_e32 v49, 0xffff0000, v49
	v_mul_f32_e32 v2, 0x3db504f3, v2
	v_mul_f32_e32 v48, 0x3db504f3, v48
	v_mul_f32_e32 v2, v2, v38
	v_mul_f32_e32 v48, v48, v39
	v_mul_f32_e32 v51, v51, v52
	v_mul_f32_e32 v49, v49, v53
	v_cndmask_b32_e32 v2, 0, v2, vcc
	v_cndmask_b32_e32 v48, 0, v48, vcc
	v_cndmask_b32_e32 v51, 0, v51, vcc
	v_cndmask_b32_e32 v49, 0, v49, vcc
	v_cvt_pk_bf16_f32 v2, v2, v48
	v_cvt_pk_bf16_f32 v51, v51, v49
	ds_write_b32 v5, v2 offset:40640
	global_store_dword v9, v2, s[14:15] offset:3072
	ds_write_b32 v16, v51 offset:3264
	v_add_u32_e32 v9, 0x1000, v9
	ds_read_b64 v[52:53], v4 offset:12288
	v_add_u32_e32 v51, 16, v3
	v_cmp_lt_i32_e32 vcc, s16, v51
	s_waitcnt vmcnt(26) lgkmcnt(0)
	v_mul_f32_e32 v38, 0x3fb8aa3b, v52
	v_mul_f32_e32 v39, 0x3fb8aa3b, v53
	v_mul_f32_e32 v52, 0xbfb8aa3b, v52
	v_mul_f32_e32 v53, 0xbfb8aa3b, v53
	v_exp_f32_e32 v38, v38
	v_exp_f32_e32 v39, v39
	v_exp_f32_e32 v52, v52
	v_exp_f32_e32 v53, v53
	v_lshlrev_b32_e32 v2, 16, v50
	v_and_b32_e32 v50, 0xffff0000, v50
	v_lshlrev_b32_e32 v51, 16, v37
	v_and_b32_e32 v37, 0xffff0000, v37
	v_mul_f32_e32 v2, 0x3db504f3, v2
	v_mul_f32_e32 v50, 0x3db504f3, v50
	v_mul_f32_e32 v2, v2, v38
	v_mul_f32_e32 v50, v50, v39
	v_mul_f32_e32 v51, v51, v52
	v_mul_f32_e32 v37, v37, v53
	v_cndmask_b32_e32 v2, 0, v2, vcc
	v_cndmask_b32_e32 v50, 0, v50, vcc
	v_cndmask_b32_e32 v51, 0, v51, vcc
	v_cndmask_b32_e32 v37, 0, v37, vcc
	v_cvt_pk_bf16_f32 v2, v2, v50
	v_cvt_pk_bf16_f32 v51, v51, v37
	ds_write_b32 v5, v2 offset:41728
	global_store_dword v9, v2, s[14:15]
	ds_write_b32 v16, v51 offset:4352
	ds_read_b64 v[52:53], v4 offset:14336
	v_add_u32_e32 v51, 20, v3
	v_cmp_lt_i32_e32 vcc, s16, v51
	s_waitcnt vmcnt(25) lgkmcnt(0)
	v_mul_f32_e32 v38, 0x3fb8aa3b, v52
	v_mul_f32_e32 v39, 0x3fb8aa3b, v53
	v_mul_f32_e32 v52, 0xbfb8aa3b, v52
	v_mul_f32_e32 v53, 0xbfb8aa3b, v53
	v_exp_f32_e32 v38, v38
	v_exp_f32_e32 v39, v39
	v_exp_f32_e32 v52, v52
	v_exp_f32_e32 v53, v53
	v_lshlrev_b32_e32 v2, 16, v36
	v_and_b32_e32 v36, 0xffff0000, v36
	v_lshlrev_b32_e32 v51, 16, v35
	v_and_b32_e32 v35, 0xffff0000, v35
	v_mul_f32_e32 v2, 0x3db504f3, v2
	v_mul_f32_e32 v36, 0x3db504f3, v36
	v_mul_f32_e32 v2, v2, v38
	v_mul_f32_e32 v36, v36, v39
	v_mul_f32_e32 v51, v51, v52
	v_mul_f32_e32 v35, v35, v53
	v_cndmask_b32_e32 v2, 0, v2, vcc
	v_cndmask_b32_e32 v36, 0, v36, vcc
	v_cndmask_b32_e32 v51, 0, v51, vcc
	v_cndmask_b32_e32 v35, 0, v35, vcc
	v_cvt_pk_bf16_f32 v2, v2, v36
	v_cvt_pk_bf16_f32 v51, v51, v35
	ds_write_b32 v5, v2 offset:42816
	global_store_dword v9, v2, s[14:15] offset:1024
	ds_write_b32 v16, v51 offset:5440
	ds_read_b64 v[52:53], v4 offset:16384
	v_add_u32_e32 v51, 24, v3
	v_cmp_lt_i32_e32 vcc, s16, v51
	s_waitcnt vmcnt(24) lgkmcnt(0)
	v_mul_f32_e32 v38, 0x3fb8aa3b, v52
	v_mul_f32_e32 v39, 0x3fb8aa3b, v53
	v_mul_f32_e32 v52, 0xbfb8aa3b, v52
	v_mul_f32_e32 v53, 0xbfb8aa3b, v53
	v_exp_f32_e32 v38, v38
	v_exp_f32_e32 v39, v39
	v_exp_f32_e32 v52, v52
	v_exp_f32_e32 v53, v53
	v_lshlrev_b32_e32 v2, 16, v34
	v_and_b32_e32 v34, 0xffff0000, v34
	v_lshlrev_b32_e32 v51, 16, v33
	v_and_b32_e32 v33, 0xffff0000, v33
	v_mul_f32_e32 v2, 0x3db504f3, v2
	v_mul_f32_e32 v34, 0x3db504f3, v34
	v_mul_f32_e32 v2, v2, v38
	v_mul_f32_e32 v34, v34, v39
	v_mul_f32_e32 v51, v51, v52
	v_mul_f32_e32 v33, v33, v53
	v_cndmask_b32_e32 v2, 0, v2, vcc
	v_cndmask_b32_e32 v34, 0, v34, vcc
	v_cndmask_b32_e32 v51, 0, v51, vcc
	v_cndmask_b32_e32 v33, 0, v33, vcc
	v_cvt_pk_bf16_f32 v2, v2, v34
	v_cvt_pk_bf16_f32 v51, v51, v33
	ds_write_b32 v5, v2 offset:43904
	global_store_dword v9, v2, s[14:15] offset:2048
	ds_write_b32 v16, v51 offset:6528
	ds_read_b64 v[52:53], v4 offset:18432
	v_add_u32_e32 v51, 28, v3
	v_cmp_lt_i32_e32 vcc, s16, v51
	s_waitcnt vmcnt(23) lgkmcnt(0)
	v_mul_f32_e32 v38, 0x3fb8aa3b, v52
	v_mul_f32_e32 v39, 0x3fb8aa3b, v53
	v_mul_f32_e32 v52, 0xbfb8aa3b, v52
	v_mul_f32_e32 v53, 0xbfb8aa3b, v53
	v_exp_f32_e32 v38, v38
	v_exp_f32_e32 v39, v39
	v_exp_f32_e32 v52, v52
	v_exp_f32_e32 v53, v53
	v_lshlrev_b32_e32 v2, 16, v32
	v_and_b32_e32 v32, 0xffff0000, v32
	v_lshlrev_b32_e32 v51, 16, v31
	v_and_b32_e32 v31, 0xffff0000, v31
	v_mul_f32_e32 v2, 0x3db504f3, v2
	v_mul_f32_e32 v32, 0x3db504f3, v32
	v_mul_f32_e32 v2, v2, v38
	v_mul_f32_e32 v32, v32, v39
	v_mul_f32_e32 v51, v51, v52
	v_mul_f32_e32 v31, v31, v53
	v_cndmask_b32_e32 v2, 0, v2, vcc
	v_cndmask_b32_e32 v32, 0, v32, vcc
	v_cndmask_b32_e32 v51, 0, v51, vcc
	v_cndmask_b32_e32 v31, 0, v31, vcc
	v_cvt_pk_bf16_f32 v2, v2, v32
	v_cvt_pk_bf16_f32 v51, v51, v31
	ds_write_b32 v5, v2 offset:44992
	global_store_dword v9, v2, s[14:15] offset:3072
	ds_write_b32 v16, v51 offset:7616
	v_add_u32_e32 v9, 0x1000, v9
	ds_read_b64 v[52:53], v4 offset:20480
	v_add_u32_e32 v51, 32, v3
	v_cmp_lt_i32_e32 vcc, s16, v51
	s_waitcnt vmcnt(22) lgkmcnt(0)
	v_mul_f32_e32 v38, 0x3fb8aa3b, v52
	v_mul_f32_e32 v39, 0x3fb8aa3b, v53
	v_mul_f32_e32 v52, 0xbfb8aa3b, v52
	v_mul_f32_e32 v53, 0xbfb8aa3b, v53
	v_exp_f32_e32 v38, v38
	v_exp_f32_e32 v39, v39
	v_exp_f32_e32 v52, v52
	v_exp_f32_e32 v53, v53
	v_lshlrev_b32_e32 v2, 16, v30
	v_and_b32_e32 v30, 0xffff0000, v30
	v_lshlrev_b32_e32 v51, 16, v29
	v_and_b32_e32 v29, 0xffff0000, v29
	v_mul_f32_e32 v2, 0x3db504f3, v2
	v_mul_f32_e32 v30, 0x3db504f3, v30
	v_mul_f32_e32 v2, v2, v38
	v_mul_f32_e32 v30, v30, v39
	v_mul_f32_e32 v51, v51, v52
	v_mul_f32_e32 v29, v29, v53
	v_cndmask_b32_e32 v2, 0, v2, vcc
	v_cndmask_b32_e32 v30, 0, v30, vcc
	v_cndmask_b32_e32 v51, 0, v51, vcc
	v_cndmask_b32_e32 v29, 0, v29, vcc
	v_cvt_pk_bf16_f32 v2, v2, v30
	v_cvt_pk_bf16_f32 v51, v51, v29
	ds_write_b32 v5, v2 offset:46080
	global_store_dword v9, v2, s[14:15]
	ds_write_b32 v16, v51 offset:8704
	ds_read_b64 v[52:53], v4 offset:22528
	v_add_u32_e32 v51, 36, v3
	v_cmp_lt_i32_e32 vcc, s16, v51
	s_waitcnt vmcnt(21) lgkmcnt(0)
	v_mul_f32_e32 v38, 0x3fb8aa3b, v52
	v_mul_f32_e32 v39, 0x3fb8aa3b, v53
	v_mul_f32_e32 v52, 0xbfb8aa3b, v52
	v_mul_f32_e32 v53, 0xbfb8aa3b, v53
	v_exp_f32_e32 v38, v38
	v_exp_f32_e32 v39, v39
	v_exp_f32_e32 v52, v52
	v_exp_f32_e32 v53, v53
	v_lshlrev_b32_e32 v2, 16, v28
	v_and_b32_e32 v28, 0xffff0000, v28
	v_lshlrev_b32_e32 v51, 16, v27
	v_and_b32_e32 v27, 0xffff0000, v27
	v_mul_f32_e32 v2, 0x3db504f3, v2
	v_mul_f32_e32 v28, 0x3db504f3, v28
	v_mul_f32_e32 v2, v2, v38
	v_mul_f32_e32 v28, v28, v39
	v_mul_f32_e32 v51, v51, v52
	v_mul_f32_e32 v27, v27, v53
	v_cndmask_b32_e32 v2, 0, v2, vcc
	v_cndmask_b32_e32 v28, 0, v28, vcc
	v_cndmask_b32_e32 v51, 0, v51, vcc
	v_cndmask_b32_e32 v27, 0, v27, vcc
	v_cvt_pk_bf16_f32 v2, v2, v28
	v_cvt_pk_bf16_f32 v51, v51, v27
	ds_write_b32 v5, v2 offset:47168
	global_store_dword v9, v2, s[14:15] offset:1024
	ds_write_b32 v16, v51 offset:9792
	ds_read_b64 v[52:53], v4 offset:24576
	v_add_u32_e32 v51, 40, v3
	v_cmp_lt_i32_e32 vcc, s16, v51
	s_waitcnt vmcnt(20) lgkmcnt(0)
	v_mul_f32_e32 v38, 0x3fb8aa3b, v52
	v_mul_f32_e32 v39, 0x3fb8aa3b, v53
	v_mul_f32_e32 v52, 0xbfb8aa3b, v52
	v_mul_f32_e32 v53, 0xbfb8aa3b, v53
	v_exp_f32_e32 v38, v38
	v_exp_f32_e32 v39, v39
	v_exp_f32_e32 v52, v52
	v_exp_f32_e32 v53, v53
	v_lshlrev_b32_e32 v2, 16, v26
	v_and_b32_e32 v26, 0xffff0000, v26
	v_lshlrev_b32_e32 v51, 16, v25
	v_and_b32_e32 v25, 0xffff0000, v25
	v_mul_f32_e32 v2, 0x3db504f3, v2
	v_mul_f32_e32 v26, 0x3db504f3, v26
	v_mul_f32_e32 v2, v2, v38
	v_mul_f32_e32 v26, v26, v39
	v_mul_f32_e32 v51, v51, v52
	v_mul_f32_e32 v25, v25, v53
	v_cndmask_b32_e32 v2, 0, v2, vcc
	v_cndmask_b32_e32 v26, 0, v26, vcc
	v_cndmask_b32_e32 v51, 0, v51, vcc
	v_cndmask_b32_e32 v25, 0, v25, vcc
	v_cvt_pk_bf16_f32 v2, v2, v26
	v_cvt_pk_bf16_f32 v51, v51, v25
	ds_write_b32 v5, v2 offset:48256
	global_store_dword v9, v2, s[14:15] offset:2048
	ds_write_b32 v16, v51 offset:10880
	ds_read_b64 v[52:53], v4 offset:26624
	v_add_u32_e32 v51, 44, v3
	v_cmp_lt_i32_e32 vcc, s16, v51
	s_waitcnt vmcnt(19) lgkmcnt(0)
	v_mul_f32_e32 v38, 0x3fb8aa3b, v52
	v_mul_f32_e32 v39, 0x3fb8aa3b, v53
	v_mul_f32_e32 v52, 0xbfb8aa3b, v52
	v_mul_f32_e32 v53, 0xbfb8aa3b, v53
	v_exp_f32_e32 v38, v38
	v_exp_f32_e32 v39, v39
	v_exp_f32_e32 v52, v52
	v_exp_f32_e32 v53, v53
	v_lshlrev_b32_e32 v2, 16, v24
	v_and_b32_e32 v24, 0xffff0000, v24
	v_lshlrev_b32_e32 v51, 16, v23
	v_and_b32_e32 v23, 0xffff0000, v23
	v_mul_f32_e32 v2, 0x3db504f3, v2
	v_mul_f32_e32 v24, 0x3db504f3, v24
	v_mul_f32_e32 v2, v2, v38
	v_mul_f32_e32 v24, v24, v39
	v_mul_f32_e32 v51, v51, v52
	v_mul_f32_e32 v23, v23, v53
	v_cndmask_b32_e32 v2, 0, v2, vcc
	v_cndmask_b32_e32 v24, 0, v24, vcc
	v_cndmask_b32_e32 v51, 0, v51, vcc
	v_cndmask_b32_e32 v23, 0, v23, vcc
	v_cvt_pk_bf16_f32 v2, v2, v24
	v_cvt_pk_bf16_f32 v51, v51, v23
	ds_write_b32 v5, v2 offset:49344
	global_store_dword v9, v2, s[14:15] offset:3072
	ds_write_b32 v16, v51 offset:11968
	v_add_u32_e32 v9, 0x1000, v9
	ds_read_b64 v[52:53], v4 offset:28672
	v_add_u32_e32 v51, 48, v3
	v_cmp_lt_i32_e32 vcc, s16, v51
	s_waitcnt vmcnt(18) lgkmcnt(0)
	v_mul_f32_e32 v38, 0x3fb8aa3b, v52
	v_mul_f32_e32 v39, 0x3fb8aa3b, v53
	v_mul_f32_e32 v52, 0xbfb8aa3b, v52
	v_mul_f32_e32 v53, 0xbfb8aa3b, v53
	v_exp_f32_e32 v38, v38
	v_exp_f32_e32 v39, v39
	v_exp_f32_e32 v52, v52
	v_exp_f32_e32 v53, v53
	v_lshlrev_b32_e32 v2, 16, v19
	v_and_b32_e32 v19, 0xffff0000, v19
	v_lshlrev_b32_e32 v51, 16, v15
	v_and_b32_e32 v15, 0xffff0000, v15
	v_mul_f32_e32 v2, 0x3db504f3, v2
	v_mul_f32_e32 v19, 0x3db504f3, v19
	v_mul_f32_e32 v2, v2, v38
	v_mul_f32_e32 v19, v19, v39
	v_mul_f32_e32 v51, v51, v52
	v_mul_f32_e32 v15, v15, v53
	v_cndmask_b32_e32 v2, 0, v2, vcc
	v_cndmask_b32_e32 v19, 0, v19, vcc
	v_cndmask_b32_e32 v51, 0, v51, vcc
	v_cndmask_b32_e32 v15, 0, v15, vcc
	v_cvt_pk_bf16_f32 v2, v2, v19
	v_cvt_pk_bf16_f32 v51, v51, v15
	ds_write_b32 v5, v2 offset:50432
	global_store_dword v9, v2, s[14:15]
	ds_write_b32 v16, v51 offset:13056
	ds_read_b64 v[52:53], v4 offset:30720
	v_add_u32_e32 v51, 52, v3
	v_cmp_lt_i32_e32 vcc, s16, v51
	s_waitcnt vmcnt(17) lgkmcnt(0)
	v_mul_f32_e32 v38, 0x3fb8aa3b, v52
	v_mul_f32_e32 v39, 0x3fb8aa3b, v53
	v_mul_f32_e32 v52, 0xbfb8aa3b, v52
	v_mul_f32_e32 v53, 0xbfb8aa3b, v53
	v_exp_f32_e32 v38, v38
	v_exp_f32_e32 v39, v39
	v_exp_f32_e32 v52, v52
	v_exp_f32_e32 v53, v53
	v_lshlrev_b32_e32 v2, 16, v14
	v_and_b32_e32 v14, 0xffff0000, v14
	v_lshlrev_b32_e32 v51, 16, v13
	v_and_b32_e32 v13, 0xffff0000, v13
	v_mul_f32_e32 v2, 0x3db504f3, v2
	v_mul_f32_e32 v14, 0x3db504f3, v14
	v_mul_f32_e32 v2, v2, v38
	v_mul_f32_e32 v14, v14, v39
	v_mul_f32_e32 v51, v51, v52
	v_mul_f32_e32 v13, v13, v53
	v_cndmask_b32_e32 v2, 0, v2, vcc
	v_cndmask_b32_e32 v14, 0, v14, vcc
	v_cndmask_b32_e32 v51, 0, v51, vcc
	v_cndmask_b32_e32 v13, 0, v13, vcc
	v_cvt_pk_bf16_f32 v2, v2, v14
	v_cvt_pk_bf16_f32 v51, v51, v13
	ds_write_b32 v5, v2 offset:51520
	global_store_dword v9, v2, s[14:15] offset:1024
	ds_write_b32 v16, v51 offset:14144
	ds_read_b64 v[52:53], v4 offset:32768
	v_add_u32_e32 v51, 56, v3
	v_cmp_lt_i32_e32 vcc, s16, v51
	s_waitcnt vmcnt(16) lgkmcnt(0)
	v_mul_f32_e32 v38, 0x3fb8aa3b, v52
	v_mul_f32_e32 v39, 0x3fb8aa3b, v53
	v_mul_f32_e32 v52, 0xbfb8aa3b, v52
	v_mul_f32_e32 v53, 0xbfb8aa3b, v53
	v_exp_f32_e32 v38, v38
	v_exp_f32_e32 v39, v39
	v_exp_f32_e32 v52, v52
	v_exp_f32_e32 v53, v53
	v_lshlrev_b32_e32 v2, 16, v11
	v_and_b32_e32 v11, 0xffff0000, v11
	v_lshlrev_b32_e32 v51, 16, v10
	v_and_b32_e32 v10, 0xffff0000, v10
	v_mul_f32_e32 v2, 0x3db504f3, v2
	v_mul_f32_e32 v11, 0x3db504f3, v11
	v_mul_f32_e32 v2, v2, v38
	v_mul_f32_e32 v11, v11, v39
	v_mul_f32_e32 v51, v51, v52
	v_mul_f32_e32 v10, v10, v53
	v_cndmask_b32_e32 v2, 0, v2, vcc
	v_cndmask_b32_e32 v11, 0, v11, vcc
	v_cndmask_b32_e32 v51, 0, v51, vcc
	v_cndmask_b32_e32 v10, 0, v10, vcc
	v_cvt_pk_bf16_f32 v2, v2, v11
	v_cvt_pk_bf16_f32 v51, v51, v10
	ds_write_b32 v5, v2 offset:52608
	global_store_dword v9, v2, s[14:15] offset:2048
	ds_write_b32 v16, v51 offset:15232
	ds_read_b64 v[52:53], v4 offset:34816
	v_add_u32_e32 v51, 60, v3
	v_cmp_lt_i32_e32 vcc, s16, v51
	s_waitcnt vmcnt(15) lgkmcnt(0)
	v_mul_f32_e32 v38, 0x3fb8aa3b, v52
	v_mul_f32_e32 v39, 0x3fb8aa3b, v53
	v_mul_f32_e32 v52, 0xbfb8aa3b, v52
	v_mul_f32_e32 v53, 0xbfb8aa3b, v53
	v_exp_f32_e32 v38, v38
	v_exp_f32_e32 v39, v39
	v_exp_f32_e32 v52, v52
	v_exp_f32_e32 v53, v53
	v_lshlrev_b32_e32 v2, 16, v8
	v_and_b32_e32 v8, 0xffff0000, v8
	v_lshlrev_b32_e32 v51, 16, v1
	v_and_b32_e32 v1, 0xffff0000, v1
	v_mul_f32_e32 v2, 0x3db504f3, v2
	v_mul_f32_e32 v8, 0x3db504f3, v8
	v_mul_f32_e32 v2, v2, v38
	v_mul_f32_e32 v8, v8, v39
	v_mul_f32_e32 v51, v51, v52
	v_mul_f32_e32 v1, v1, v53
	v_cndmask_b32_e32 v2, 0, v2, vcc
	v_cndmask_b32_e32 v8, 0, v8, vcc
	v_cndmask_b32_e32 v51, 0, v51, vcc
	v_cndmask_b32_e32 v1, 0, v1, vcc
	v_cvt_pk_bf16_f32 v2, v2, v8
	v_cvt_pk_bf16_f32 v51, v51, v1
	ds_write_b32 v5, v2 offset:53696
	global_store_dword v9, v2, s[14:15] offset:3072
	ds_write_b32 v16, v51 offset:16320
	s_movk_i32 s14, 0x800
	v_cmp_gt_i32_e32 vcc, s14, v0
	s_waitcnt lgkmcnt(0)
	s_barrier
	s_and_saveexec_b64 s[14:15], vcc
	s_cbranch_execz .LBB0_2003
	s_lshl_b64 s[16:17], s[12:13], 1
	s_add_u32 s16, s2, s16
	s_addc_u32 s17, s3, s17
	s_mov_b64 s[18:19], 0
	v_mov_b32_e32 v1, v12
	v_mov_b32_e32 v2, v0
